# G1/G4 mainloop restaged: 64-deep K chunks, every LDS-DMA fetches whole 128-byte lines (A half-chunk ring of 3, B fragments held in registers)
# speedup vs baseline: 1.0436x; 1.0422x over previous
.LBB1_54:
	v_readlane_b32 s4, v242, 0
	s_lshl_b32 s5, s2, 3
	s_and_b32 s6, s4, 7
	s_or_b32 s5, s6, s5
	s_mul_i32 s5, s5, s55
	s_ashr_i32 s4, s4, 3
	s_add_i32 s4, s5, s4
	s_cmpk_lt_i32 s4, 0x400
	s_mov_b64 s[40:41], -1
	s_cbranch_scc0 .LBB1_53
	s_ashr_i32 s5, s4, 31
	s_lshr_b32 s5, s5, 25
	s_add_i32 s5, s4, s5
	s_and_b32 s6, s5, 0xffffff80
	s_sub_i32 s7, s4, s6
	s_ashr_i32 s4, s7, 31
	s_lshr_b32 s4, s4, 29
	s_add_i32 s6, s7, s4
	s_and_b32 s4, s6, 0xfffff8
	s_sub_i32 s4, s7, s4
	s_lshl_b32 s5, s5, 4
	s_and_b32 s5, s5, 0xfffff800
	s_lshl_b32 s4, s4, 8
	s_add_i32 s4, s4, s5
	s_lshl_b32 s5, s6, 4
	v_mov_b32_e32 v134, v162
	s_and_b32 s40, s5, 0xffffff80
	s_movk_i32 s10, 0x78
	v_readfirstlane_b32 s5, v134
	v_lshrrev_b32_e32 v0, 3, v134
	v_and_b32_e32 v0, 6, v0
	s_and_b32 s8, s5, 0xffffffc0
	s_waitcnt lgkmcnt(0)
	v_bfe_u32 v2, v134, 2, 4
	v_lshrrev_b32_e64 v0, v0, s10
	s_add_i32 s8, s8, s4
	v_xor_b32_e32 v3, v0, v134
	v_or_b32_e32 v0, s8, v2
	v_ashrrev_i32_e32 v1, 31, v0
	v_lshlrev_b64 v[0:1], 11, v[0:1]
	v_lshlrev_b32_e32 v3, 4, v3
	v_lshl_add_u64 v[0:1], s[74:75], 0, v[0:1]
	v_and_b32_e32 v128, 48, v3
	s_load_dwordx16 s[80:95], s[0:1], 0xc0
	s_ashr_i32 s6, s5, 6
	v_lshl_add_u64 v[130:131], v[0:1], 0, v[128:129]
	v_or_b32_e32 v0, s40, v2
	v_lshl_add_u32 v0, s6, 5, v0
	v_ashrrev_i32_e32 v1, 31, v0
	v_lshlrev_b64 v[0:1], 11, v[0:1]
	s_waitcnt lgkmcnt(0)
	v_lshl_add_u64 v[0:1], s[92:93], 0, v[0:1]
	v_lshl_add_u64 v[132:133], v[0:1], 0, v[128:129]
	v_lshrrev_b32_e32 v0, 1, v134
	v_and_b32_e32 v0, 6, v0
	v_bfe_u32 v136, v134, 4, 2
	s_lshl_b32 s8, s6, 12
	v_lshrrev_b32_e64 v0, v0, s10
	v_and_b32_e32 v135, 15, v134
	s_lshl_b32 s9, s6, 11
	s_and_b32 s6, s5, 0xffffff80
	v_bitop3_b32 v0, v0, v136, 3 bitop3:0x6c
	s_and_b32 s5, s5, 64
	s_add_i32 s10, s8, 16
	v_lshlrev_b32_e32 v138, 4, v0
	v_or_b32_e32 v0, s5, v135
	s_mov_b32 m0, s10
	v_lshlrev_b32_e32 v139, 6, v0
	s_barrier
	v_lshl_add_u64 v[0:1], v[130:131], 0, s[34:35]
	s_add_i32 m0, s10, 0x400
	s_mov_b64 s[12:13], 0x10000
	v_lshl_add_u64 v[0:1], v[130:131], 0, s[12:13]
	s_add_i32 m0, s10, 0x800
	s_mov_b64 s[12:13], 0x18000
	v_lshl_add_u64 v[0:1], v[130:131], 0, s[12:13]
	s_add_i32 m0, s10, 0xc00
	s_sub_i32 s11, s10, s9
	s_add_i32 m0, s11, 0x4000
	v_lshl_add_u64 v[0:1], v[132:133], 0, s[34:35]
	s_add_i32 m0, s11, 0x4400
	s_mov_b64 s[12:13], 0x8040
	v_lshl_add_u64 v[0:1], v[130:131], 0, 64
	s_add_i32 m0, s10, 0x6000
	s_mov_b64 s[14:15], 0x10040
	v_lshl_add_u64 v[0:1], v[130:131], 0, s[12:13]
	s_add_i32 m0, s10, 0x6400
	v_or_b32_e32 v128, s6, v135
	v_lshl_add_u64 v[0:1], v[130:131], 0, s[14:15]
	s_add_i32 m0, s10, 0x6800
	s_mov_b64 s[14:15], 0x18040
	v_lshl_add_u64 v[0:1], v[130:131], 0, s[14:15]
	s_add_i32 m0, s10, 0x6c00
	v_lshlrev_b32_e32 v137, 6, v128
	v_lshl_add_u64 v[0:1], v[132:133], 0, 64
	s_add_i32 m0, s11, 0xa000
	s_mov_b32 s10, 0
	v_lshl_add_u64 v[0:1], v[132:133], 0, s[12:13]
	s_add_i32 m0, s11, 0xa400
	s_mov_b32 s11, 0
	v_mov_b32_e32 v0, 0
	v_mov_b32_e32 v1, v0
	v_mov_b32_e32 v2, v0
	v_mov_b32_e32 v3, v0
	v_mov_b32_e32 v4, v0
	v_mov_b32_e32 v5, v0
	v_mov_b32_e32 v6, v0
	v_mov_b32_e32 v7, v0
	v_mov_b32_e32 v8, v0
	v_mov_b32_e32 v9, v0
	v_mov_b32_e32 v10, v0
	v_mov_b32_e32 v11, v0
	v_mov_b32_e32 v12, v0
	v_mov_b32_e32 v13, v0
	v_mov_b32_e32 v14, v0
	v_mov_b32_e32 v15, v0
	v_mov_b32_e32 v16, v0
	v_mov_b32_e32 v17, v0
	v_mov_b32_e32 v18, v0
	v_mov_b32_e32 v19, v0
	v_mov_b32_e32 v20, v0
	v_mov_b32_e32 v21, v0
	v_mov_b32_e32 v22, v0
	v_mov_b32_e32 v23, v0
	v_mov_b32_e32 v24, v0
	v_mov_b32_e32 v25, v0
	v_mov_b32_e32 v26, v0
	v_mov_b32_e32 v27, v0
	v_mov_b32_e32 v28, v0
	v_mov_b32_e32 v29, v0
	v_mov_b32_e32 v30, v0
	v_mov_b32_e32 v31, v0
	v_mov_b32_e32 v32, v0
	v_mov_b32_e32 v33, v0
	v_mov_b32_e32 v34, v0
	v_mov_b32_e32 v35, v0
	v_mov_b32_e32 v36, v0
	v_mov_b32_e32 v37, v0
	v_mov_b32_e32 v38, v0
	v_mov_b32_e32 v39, v0
	v_mov_b32_e32 v40, v0
	v_mov_b32_e32 v41, v0
	v_mov_b32_e32 v42, v0
	v_mov_b32_e32 v43, v0
	v_mov_b32_e32 v44, v0
	v_mov_b32_e32 v45, v0
	v_mov_b32_e32 v46, v0
	v_mov_b32_e32 v47, v0
	v_mov_b32_e32 v48, v0
	v_mov_b32_e32 v49, v0
	v_mov_b32_e32 v50, v0
	v_mov_b32_e32 v51, v0
	v_mov_b32_e32 v52, v0
	v_mov_b32_e32 v53, v0
	v_mov_b32_e32 v54, v0
	v_mov_b32_e32 v55, v0
	v_mov_b32_e32 v56, v0
	v_mov_b32_e32 v57, v0
	v_mov_b32_e32 v58, v0
	v_mov_b32_e32 v59, v0
	v_mov_b32_e32 v60, v0
	v_mov_b32_e32 v61, v0
	v_mov_b32_e32 v62, v0
	v_mov_b32_e32 v63, v0
	v_mov_b32_e32 v64, v0
	v_mov_b32_e32 v65, v0
	v_mov_b32_e32 v66, v0
	v_mov_b32_e32 v67, v0
	v_mov_b32_e32 v68, v0
	v_mov_b32_e32 v69, v0
	v_mov_b32_e32 v70, v0
	v_mov_b32_e32 v71, v0
	v_mov_b32_e32 v72, v0
	v_mov_b32_e32 v73, v0
	v_mov_b32_e32 v74, v0
	v_mov_b32_e32 v75, v0
	v_mov_b32_e32 v84, v0
	v_mov_b32_e32 v85, v0
	v_mov_b32_e32 v86, v0
	v_mov_b32_e32 v87, v0
	v_mov_b32_e32 v96, v0
	v_mov_b32_e32 v97, v0
	v_mov_b32_e32 v98, v0
	v_mov_b32_e32 v99, v0
	v_mov_b32_e32 v100, v0
	v_mov_b32_e32 v101, v0
	v_mov_b32_e32 v102, v0
	v_mov_b32_e32 v103, v0
	v_mov_b32_e32 v104, v0
	v_mov_b32_e32 v105, v0
	v_mov_b32_e32 v106, v0
	v_mov_b32_e32 v107, v0
	v_mov_b32_e32 v108, v0
	v_mov_b32_e32 v109, v0
	v_mov_b32_e32 v110, v0
	v_mov_b32_e32 v111, v0
	v_mov_b32_e32 v112, v0
	v_mov_b32_e32 v113, v0
	v_mov_b32_e32 v114, v0
	v_mov_b32_e32 v115, v0
	v_mov_b32_e32 v116, v0
	v_mov_b32_e32 v117, v0
	v_mov_b32_e32 v118, v0
	v_mov_b32_e32 v119, v0
	v_mov_b32_e32 v120, v0
	v_mov_b32_e32 v121, v0
	v_mov_b32_e32 v122, v0
	v_mov_b32_e32 v123, v0
	v_mov_b32_e32 v124, v0
	v_mov_b32_e32 v125, v0
	v_mov_b32_e32 v126, v0
	v_mov_b32_e32 v127, v0
	v_mov_b32_e32 v76, v0
	v_mov_b32_e32 v77, v0
	v_mov_b32_e32 v78, v0
	v_mov_b32_e32 v79, v0
	v_mov_b32_e32 v80, v0
	v_mov_b32_e32 v81, v0
	v_mov_b32_e32 v82, v0
	v_mov_b32_e32 v83, v0
	v_mov_b32_e32 v88, v0
	v_mov_b32_e32 v89, v0
	v_mov_b32_e32 v90, v0
	v_mov_b32_e32 v91, v0
	v_mov_b32_e32 v92, v0
	v_mov_b32_e32 v93, v0
	v_mov_b32_e32 v94, v0
	v_mov_b32_e32 v95, v0
	s_mov_b64 s[16:17], 0x10080
	v_and_b32_e32 v204, 15, v168
	v_lshrrev_b32_e32 v205, 4, v168
	v_bfe_u32 v206, v168, 1, 3
	v_xor_b32_e32 v205, v205, v206
	v_lshlrev_b32_e32 v205, 4, v205
	v_readfirstlane_b32 s15, v162
	v_readfirstlane_b32 s18, v130
	v_readfirstlane_b32 s19, v131
	v_readfirstlane_b32 s28, v132
	v_readfirstlane_b32 s29, v133
	s_lshr_b32 s15, s15, 6
	s_lshl_b32 s54, s15, 12
	s_lshr_b32 s41, s15, 1
	s_and_b32 s42, s15, 1
	v_lshl_add_u32 v206, s41, 6, v204
	v_lshl_add_u32 v196, v206, 7, v205
	v_xor_b32_e32 v197, 64, v196
	v_lshl_add_u32 v206, s42, 6, v204
	v_lshl_add_u32 v198, v206, 7, v205
	v_xor_b32_e32 v199, 64, v198
	v_add_u32_e32 v198, 0xc010, v198
	v_add_u32_e32 v199, 0xc010, v199
	v_lshrrev_b32_e32 v206, 3, v168
	v_and_b32_e32 v207, 7, v168
	v_lshrrev_b32_e32 v204, 1, v206
	v_xor_b32_e32 v207, v207, v204
	v_lshlrev_b32_e32 v207, 4, v207
	v_lshl_add_u32 v200, v206, 11, v207
	v_xor_b32_e32 v201, 64, v200
	s_lshl_b32 s42, s42, 16
	s_sub_u32 s18, s18, s42
	s_subb_u32 s19, s19, 0
	s_add_i32 s41, s54, 16
	s_add_i32 m0, s41, 0x0
	s_nop 0
	global_load_lds_dwordx4 v200, s[18:19]
	s_add_i32 m0, s41, 0x400
	s_add_u32 s52, s18, 0x4000
	s_addc_u32 s53, s19, 0
	global_load_lds_dwordx4 v201, s[52:53]
	s_add_i32 m0, s41, 0x800
	s_add_u32 s52, s18, 0x8000
	s_addc_u32 s53, s19, 0
	global_load_lds_dwordx4 v200, s[52:53]
	s_add_i32 m0, s41, 0xc00
	s_add_u32 s52, s18, 0xc000
	s_addc_u32 s53, s19, 0
	global_load_lds_dwordx4 v201, s[52:53]
	s_add_i32 m0, s54, 0xc010
	s_nop 0
	global_load_lds_dwordx4 v200, s[28:29]
	s_add_i32 m0, s54, 0xc410
	s_add_u32 s52, s28, 0x4000
	s_addc_u32 s53, s29, 0
	global_load_lds_dwordx4 v201, s[52:53]
	s_add_i32 m0, s54, 0xc810
	s_add_u32 s52, s28, 0x8000
	s_addc_u32 s53, s29, 0
	global_load_lds_dwordx4 v200, s[52:53]
	s_add_i32 m0, s54, 0xcc10
	s_add_u32 s52, s28, 0xc000
	s_addc_u32 s53, s29, 0
	global_load_lds_dwordx4 v201, s[52:53]
	s_add_u32 s50, s18, 0x20000
	s_addc_u32 s51, s19, 0
	s_add_i32 m0, s41, 0x4000
	s_nop 0
	global_load_lds_dwordx4 v200, s[50:51]
	s_add_i32 m0, s41, 0x4400
	s_add_u32 s52, s50, 0x4000
	s_addc_u32 s53, s51, 0
	global_load_lds_dwordx4 v201, s[52:53]
	s_add_i32 m0, s41, 0x4800
	s_add_u32 s52, s50, 0x8000
	s_addc_u32 s53, s51, 0
	global_load_lds_dwordx4 v200, s[52:53]
	s_add_i32 m0, s41, 0x4c00
	s_add_u32 s52, s50, 0xc000
	s_addc_u32 s53, s51, 0
	global_load_lds_dwordx4 v201, s[52:53]
	s_mov_b32 s13, 0
	s_mov_b32 s14, 0
	s_setprio 1
.LBB1_56:
	s_mul_i32 s15, s13, 0x4000
	s_add_i32 s15, s15, 16
	s_add_i32 s41, s13, 2
	s_cmp_ge_u32 s41, 3
	s_cselect_b32 s42, 3, 0
	s_sub_i32 s41, s41, s42
	s_mul_i32 s41, s41, 0x4000
	s_add_i32 s41, s41, 16
	s_add_i32 s41, s41, s54
	s_add_i32 s32, s14, 1
	s_min_u32 s32, s32, 15
	s_lshl_b32 s32, s32, 7
	s_add_u32 s50, s18, s32
	s_addc_u32 s51, s19, 0
	s_waitcnt vmcnt(4)
	s_barrier
	v_add_u32_e32 v202, s15, v196
	v_add_u32_e32 v203, s15, v197
	ds_read_b128 v[140:143], v198 offset:0
	ds_read_b128 v[144:147], v198 offset:2048
	ds_read_b128 v[148:151], v198 offset:4096
	ds_read_b128 v[152:155], v198 offset:6144
	ds_read_b128 v[156:159], v202
	ds_read_b128 v[216:219], v199 offset:0
	ds_read_b128 v[220:223], v199 offset:2048
	ds_read_b128 v[224:227], v199 offset:4096
	ds_read_b128 v[228:231], v199 offset:6144
	ds_read_b128 v[188:191], v203
	ds_read_b128 v[192:195], v202 offset:2048
	ds_read_b128 v[208:211], v203 offset:2048
	s_waitcnt lgkmcnt(7)
	s_add_i32 m0, s41, 0x0
	v_mfma_f32_16x16x32_bf16 v[124:127], v[140:143], v[156:159], v[124:127]
	v_mfma_f32_16x16x32_bf16 v[120:123], v[144:147], v[156:159], v[120:123]
	v_mfma_f32_16x16x32_bf16 v[116:119], v[148:151], v[156:159], v[116:119]
	v_mfma_f32_16x16x32_bf16 v[112:115], v[152:155], v[156:159], v[112:115]
	ds_read_b128 v[156:159], v202 offset:4096
	global_load_lds_dwordx4 v200, s[50:51]
	s_waitcnt lgkmcnt(3)
	s_add_i32 m0, s41, 0x400
	s_add_u32 s52, s50, 0x4000
	s_addc_u32 s53, s51, 0
	v_mfma_f32_16x16x32_bf16 v[124:127], v[216:219], v[188:191], v[124:127]
	v_mfma_f32_16x16x32_bf16 v[120:123], v[220:223], v[188:191], v[120:123]
	v_mfma_f32_16x16x32_bf16 v[116:119], v[224:227], v[188:191], v[116:119]
	v_mfma_f32_16x16x32_bf16 v[112:115], v[228:231], v[188:191], v[112:115]
	ds_read_b128 v[188:191], v203 offset:4096
	global_load_lds_dwordx4 v201, s[52:53]
	s_waitcnt lgkmcnt(3)
	s_add_i32 m0, s41, 0x800
	s_add_u32 s52, s50, 0x8000
	s_addc_u32 s53, s51, 0
	v_mfma_f32_16x16x32_bf16 v[108:111], v[140:143], v[192:195], v[108:111]
	v_mfma_f32_16x16x32_bf16 v[104:107], v[144:147], v[192:195], v[104:107]
	v_mfma_f32_16x16x32_bf16 v[100:103], v[148:151], v[192:195], v[100:103]
	v_mfma_f32_16x16x32_bf16 v[96:99], v[152:155], v[192:195], v[96:99]
	ds_read_b128 v[192:195], v202 offset:6144
	global_load_lds_dwordx4 v200, s[52:53]
	s_waitcnt lgkmcnt(3)
	s_add_i32 m0, s41, 0xc00
	s_add_u32 s52, s50, 0xc000
	s_addc_u32 s53, s51, 0
	v_mfma_f32_16x16x32_bf16 v[108:111], v[216:219], v[208:211], v[108:111]
	v_mfma_f32_16x16x32_bf16 v[104:107], v[220:223], v[208:211], v[104:107]
	v_mfma_f32_16x16x32_bf16 v[100:103], v[224:227], v[208:211], v[100:103]
	v_mfma_f32_16x16x32_bf16 v[96:99], v[228:231], v[208:211], v[96:99]
	ds_read_b128 v[208:211], v203 offset:6144
	global_load_lds_dwordx4 v201, s[52:53]
	s_waitcnt lgkmcnt(3)
	v_mfma_f32_16x16x32_bf16 v[84:87], v[140:143], v[156:159], v[84:87]
	v_mfma_f32_16x16x32_bf16 v[72:75], v[144:147], v[156:159], v[72:75]
	v_mfma_f32_16x16x32_bf16 v[68:71], v[148:151], v[156:159], v[68:71]
	v_mfma_f32_16x16x32_bf16 v[64:67], v[152:155], v[156:159], v[64:67]
	s_waitcnt lgkmcnt(2)
	v_mfma_f32_16x16x32_bf16 v[84:87], v[216:219], v[188:191], v[84:87]
	v_mfma_f32_16x16x32_bf16 v[72:75], v[220:223], v[188:191], v[72:75]
	v_mfma_f32_16x16x32_bf16 v[68:71], v[224:227], v[188:191], v[68:71]
	v_mfma_f32_16x16x32_bf16 v[64:67], v[228:231], v[188:191], v[64:67]
	s_waitcnt lgkmcnt(1)
	v_mfma_f32_16x16x32_bf16 v[60:63], v[140:143], v[192:195], v[60:63]
	v_mfma_f32_16x16x32_bf16 v[56:59], v[144:147], v[192:195], v[56:59]
	v_mfma_f32_16x16x32_bf16 v[52:55], v[148:151], v[192:195], v[52:55]
	v_mfma_f32_16x16x32_bf16 v[48:51], v[152:155], v[192:195], v[48:51]
	s_waitcnt lgkmcnt(0)
	v_mfma_f32_16x16x32_bf16 v[60:63], v[216:219], v[208:211], v[60:63]
	v_mfma_f32_16x16x32_bf16 v[56:59], v[220:223], v[208:211], v[56:59]
	v_mfma_f32_16x16x32_bf16 v[52:55], v[224:227], v[208:211], v[52:55]
	v_mfma_f32_16x16x32_bf16 v[48:51], v[228:231], v[208:211], v[48:51]
	s_add_i32 s42, s13, 1
	s_cmp_lg_u32 s13, 2
	s_cselect_b32 s13, s42, 0
	s_mul_i32 s15, s13, 0x4000
	s_add_i32 s15, s15, 16
	s_add_i32 s41, s13, 2
	s_cmp_ge_u32 s41, 3
	s_cselect_b32 s42, 3, 0
	s_sub_i32 s41, s41, s42
	s_mul_i32 s41, s41, 0x4000
	s_add_i32 s41, s41, 16
	s_add_i32 s41, s41, s54
	s_add_u32 s50, s18, s32
	s_addc_u32 s51, s19, 0
	s_add_u32 s50, s50, 0x20000
	s_addc_u32 s51, s51, 0
	s_add_u32 s46, s28, s32
	s_addc_u32 s47, s29, 0
	s_waitcnt vmcnt(4)
	s_barrier
	v_add_u32_e32 v202, s15, v196
	v_add_u32_e32 v203, s15, v197
	ds_read_b128 v[156:159], v202
	ds_read_b128 v[188:191], v203
	ds_read_b128 v[192:195], v202 offset:2048
	ds_read_b128 v[208:211], v203 offset:2048
	s_waitcnt lgkmcnt(3)
	s_add_i32 m0, s54, 0xc010
	v_mfma_f32_16x16x32_bf16 v[44:47], v[140:143], v[156:159], v[44:47]
	v_mfma_f32_16x16x32_bf16 v[40:43], v[144:147], v[156:159], v[40:43]
	v_mfma_f32_16x16x32_bf16 v[36:39], v[148:151], v[156:159], v[36:39]
	v_mfma_f32_16x16x32_bf16 v[32:35], v[152:155], v[156:159], v[32:35]
	ds_read_b128 v[156:159], v202 offset:4096
	global_load_lds_dwordx4 v200, s[46:47]
	s_waitcnt lgkmcnt(3)
	s_add_i32 m0, s54, 0xc410
	s_add_u32 s52, s46, 0x4000
	s_addc_u32 s53, s47, 0
	v_mfma_f32_16x16x32_bf16 v[44:47], v[216:219], v[188:191], v[44:47]
	v_mfma_f32_16x16x32_bf16 v[40:43], v[220:223], v[188:191], v[40:43]
	v_mfma_f32_16x16x32_bf16 v[36:39], v[224:227], v[188:191], v[36:39]
	v_mfma_f32_16x16x32_bf16 v[32:35], v[228:231], v[188:191], v[32:35]
	ds_read_b128 v[188:191], v203 offset:4096
	global_load_lds_dwordx4 v201, s[52:53]
	s_waitcnt lgkmcnt(3)
	s_add_i32 m0, s54, 0xc810
	s_add_u32 s52, s46, 0x8000
	s_addc_u32 s53, s47, 0
	v_mfma_f32_16x16x32_bf16 v[28:31], v[140:143], v[192:195], v[28:31]
	v_mfma_f32_16x16x32_bf16 v[24:27], v[144:147], v[192:195], v[24:27]
	v_mfma_f32_16x16x32_bf16 v[20:23], v[148:151], v[192:195], v[20:23]
	v_mfma_f32_16x16x32_bf16 v[16:19], v[152:155], v[192:195], v[16:19]
	ds_read_b128 v[192:195], v202 offset:6144
	global_load_lds_dwordx4 v200, s[52:53]
	s_waitcnt lgkmcnt(3)
	s_add_i32 m0, s54, 0xcc10
	s_add_u32 s52, s46, 0xc000
	s_addc_u32 s53, s47, 0
	v_mfma_f32_16x16x32_bf16 v[28:31], v[216:219], v[208:211], v[28:31]
	v_mfma_f32_16x16x32_bf16 v[24:27], v[220:223], v[208:211], v[24:27]
	v_mfma_f32_16x16x32_bf16 v[20:23], v[224:227], v[208:211], v[20:23]
	v_mfma_f32_16x16x32_bf16 v[16:19], v[228:231], v[208:211], v[16:19]
	ds_read_b128 v[208:211], v203 offset:6144
	global_load_lds_dwordx4 v201, s[52:53]
	s_waitcnt lgkmcnt(3)
	s_add_i32 m0, s41, 0x0
	v_mfma_f32_16x16x32_bf16 v[12:15], v[140:143], v[156:159], v[12:15]
	v_mfma_f32_16x16x32_bf16 v[8:11], v[144:147], v[156:159], v[8:11]
	v_mfma_f32_16x16x32_bf16 v[4:7], v[148:151], v[156:159], v[4:7]
	v_mfma_f32_16x16x32_bf16 v[0:3], v[152:155], v[156:159], v[0:3]
	global_load_lds_dwordx4 v200, s[50:51]
	s_waitcnt lgkmcnt(2)
	s_add_i32 m0, s41, 0x400
	s_add_u32 s52, s50, 0x4000
	s_addc_u32 s53, s51, 0
	v_mfma_f32_16x16x32_bf16 v[12:15], v[216:219], v[188:191], v[12:15]
	v_mfma_f32_16x16x32_bf16 v[8:11], v[220:223], v[188:191], v[8:11]
	v_mfma_f32_16x16x32_bf16 v[4:7], v[224:227], v[188:191], v[4:7]
	v_mfma_f32_16x16x32_bf16 v[0:3], v[228:231], v[188:191], v[0:3]
	global_load_lds_dwordx4 v201, s[52:53]
	s_waitcnt lgkmcnt(1)
	s_add_i32 m0, s41, 0x800
	s_add_u32 s52, s50, 0x8000
	s_addc_u32 s53, s51, 0
	v_mfma_f32_16x16x32_bf16 v[76:79], v[140:143], v[192:195], v[76:79]
	v_mfma_f32_16x16x32_bf16 v[80:83], v[144:147], v[192:195], v[80:83]
	v_mfma_f32_16x16x32_bf16 v[88:91], v[148:151], v[192:195], v[88:91]
	v_mfma_f32_16x16x32_bf16 v[92:95], v[152:155], v[192:195], v[92:95]
	global_load_lds_dwordx4 v200, s[52:53]
	s_waitcnt lgkmcnt(0)
	s_add_i32 m0, s41, 0xc00
	s_add_u32 s52, s50, 0xc000
	s_addc_u32 s53, s51, 0
	v_mfma_f32_16x16x32_bf16 v[76:79], v[216:219], v[208:211], v[76:79]
	v_mfma_f32_16x16x32_bf16 v[80:83], v[220:223], v[208:211], v[80:83]
	v_mfma_f32_16x16x32_bf16 v[88:91], v[224:227], v[208:211], v[88:91]
	v_mfma_f32_16x16x32_bf16 v[92:95], v[228:231], v[208:211], v[92:95]
	global_load_lds_dwordx4 v201, s[52:53]
	s_add_i32 s42, s13, 1
	s_cmp_lg_u32 s13, 2
	s_cselect_b32 s13, s42, 0
	s_add_i32 s14, s14, 1
	s_cmp_eq_u32 s14, 16
	s_cbranch_scc0 .LBB1_56
	s_setprio 0
	s_cmpk_lt_i32 s7, 0x80
	v_readlane_b32 s10, v242, 5
	s_waitcnt vmcnt(0)
	s_cselect_b64 s[8:9], -1, 0
	v_readlane_b32 s11, v242, 6
	s_and_b64 s[8:9], s[10:11], s[8:9]
	s_mov_b64 s[42:43], -1
	s_and_b64 vcc, exec, s[8:9]
	v_cvt_pk_bf16_f32 v124, v124, v125
	v_cvt_pk_bf16_f32 v125, v126, v127
	v_cvt_pk_bf16_f32 v120, v120, v121
	v_cvt_pk_bf16_f32 v121, v122, v123
	v_cvt_pk_bf16_f32 v116, v116, v117
	v_cvt_pk_bf16_f32 v117, v118, v119
	v_cvt_pk_bf16_f32 v112, v112, v113
	v_cvt_pk_bf16_f32 v113, v114, v115
	v_cvt_pk_bf16_f32 v108, v108, v109
	v_cvt_pk_bf16_f32 v109, v110, v111
	v_cvt_pk_bf16_f32 v104, v104, v105
	v_cvt_pk_bf16_f32 v105, v106, v107
	v_cvt_pk_bf16_f32 v100, v100, v101
	v_cvt_pk_bf16_f32 v101, v102, v103
	v_cvt_pk_bf16_f32 v96, v96, v97
	v_cvt_pk_bf16_f32 v97, v98, v99
	v_cvt_pk_bf16_f32 v84, v84, v85
	v_cvt_pk_bf16_f32 v85, v86, v87
	v_cvt_pk_bf16_f32 v72, v72, v73
	v_cvt_pk_bf16_f32 v73, v74, v75
	v_cvt_pk_bf16_f32 v68, v68, v69
	v_cvt_pk_bf16_f32 v69, v70, v71
	v_cvt_pk_bf16_f32 v64, v64, v65
	v_cvt_pk_bf16_f32 v65, v66, v67
	v_cvt_pk_bf16_f32 v60, v60, v61
	v_cvt_pk_bf16_f32 v61, v62, v63
	v_cvt_pk_bf16_f32 v56, v56, v57
	v_cvt_pk_bf16_f32 v57, v58, v59
	v_cvt_pk_bf16_f32 v52, v52, v53
	v_cvt_pk_bf16_f32 v53, v54, v55
	v_cvt_pk_bf16_f32 v48, v48, v49
	v_cvt_pk_bf16_f32 v49, v50, v51
	v_cvt_pk_bf16_f32 v44, v44, v45
	v_cvt_pk_bf16_f32 v45, v46, v47
	v_cvt_pk_bf16_f32 v40, v40, v41
	v_cvt_pk_bf16_f32 v41, v42, v43
	v_cvt_pk_bf16_f32 v36, v36, v37
	v_cvt_pk_bf16_f32 v37, v38, v39
	v_cvt_pk_bf16_f32 v32, v32, v33
	v_cvt_pk_bf16_f32 v33, v34, v35
	v_cvt_pk_bf16_f32 v28, v28, v29
	v_cvt_pk_bf16_f32 v29, v30, v31
	v_cvt_pk_bf16_f32 v24, v24, v25
	v_cvt_pk_bf16_f32 v25, v26, v27
	v_cvt_pk_bf16_f32 v20, v20, v21
	v_cvt_pk_bf16_f32 v21, v22, v23
	v_cvt_pk_bf16_f32 v16, v16, v17
	v_cvt_pk_bf16_f32 v17, v18, v19
	v_cvt_pk_bf16_f32 v12, v12, v13
	v_cvt_pk_bf16_f32 v13, v14, v15
	v_cvt_pk_bf16_f32 v14, v8, v9
	v_cvt_pk_bf16_f32 v15, v10, v11
	v_cvt_pk_bf16_f32 v8, v4, v5
	v_cvt_pk_bf16_f32 v9, v6, v7
	v_cvt_pk_bf16_f32 v10, v0, v1
	v_cvt_pk_bf16_f32 v11, v2, v3
	v_cvt_pk_bf16_f32 v2, v76, v77
	v_cvt_pk_bf16_f32 v3, v78, v79
	v_cvt_pk_bf16_f32 v6, v80, v81
	v_cvt_pk_bf16_f32 v7, v82, v83
	v_cvt_pk_bf16_f32 v0, v88, v89
	v_cvt_pk_bf16_f32 v1, v90, v91
	v_cvt_pk_bf16_f32 v4, v92, v93
	v_cvt_pk_bf16_f32 v5, v94, v95
	s_waitcnt vmcnt(0)
	s_barrier
	s_cbranch_vccnz .LBB1_59
	s_load_dwordx16 s[64:79], s[0:1], 0x140
	v_or_b32_e32 v18, s4, v135
	v_add_u32_e32 v18, s6, v18
	v_lshl_or_b32 v19, v136, 2, s40
	v_or_b32_e32 v22, s5, v19
	v_ashrrev_i32_e32 v19, 31, v18
	v_lshlrev_b64 v[26:27], 12, v[18:19]
	v_ashrrev_i32_e32 v23, 31, v22
	s_waitcnt lgkmcnt(0)
	v_lshl_add_u64 v[26:27], s[76:77], 0, v[26:27]
	v_lshlrev_b64 v[22:23], 1, v[22:23]
	v_lshl_add_u64 v[26:27], v[26:27], 0, v[22:23]
	global_store_dwordx2 v[26:27], v[124:125], off
	global_store_dwordx2 v[26:27], v[120:121], off offset:32
	global_store_dwordx2 v[26:27], v[116:117], off offset:64
	global_store_dwordx2 v[26:27], v[112:113], off offset:96
	v_or_b32_e32 v26, 16, v18
	v_ashrrev_i32_e32 v27, 31, v26
	v_lshlrev_b64 v[26:27], 12, v[26:27]
	v_lshl_add_u64 v[26:27], s[76:77], 0, v[26:27]
	v_lshl_add_u64 v[26:27], v[26:27], 0, v[22:23]
	global_store_dwordx2 v[26:27], v[108:109], off
	global_store_dwordx2 v[26:27], v[104:105], off offset:32
	global_store_dwordx2 v[26:27], v[100:101], off offset:64
	global_store_dwordx2 v[26:27], v[96:97], off offset:96
	v_or_b32_e32 v26, 32, v18
	v_ashrrev_i32_e32 v27, 31, v26
	v_lshlrev_b64 v[26:27], 12, v[26:27]
	v_lshl_add_u64 v[26:27], s[76:77], 0, v[26:27]
	v_lshl_add_u64 v[26:27], v[26:27], 0, v[22:23]
	global_store_dwordx2 v[26:27], v[84:85], off
	global_store_dwordx2 v[26:27], v[72:73], off offset:32
	global_store_dwordx2 v[26:27], v[68:69], off offset:64
	global_store_dwordx2 v[26:27], v[64:65], off offset:96
	v_or_b32_e32 v26, 48, v18
	v_ashrrev_i32_e32 v27, 31, v26
	v_lshlrev_b64 v[26:27], 12, v[26:27]
	v_lshl_add_u64 v[26:27], s[76:77], 0, v[26:27]
	v_lshl_add_u64 v[26:27], v[26:27], 0, v[22:23]
	global_store_dwordx2 v[26:27], v[60:61], off
	global_store_dwordx2 v[26:27], v[56:57], off offset:32
	global_store_dwordx2 v[26:27], v[52:53], off offset:64
	global_store_dwordx2 v[26:27], v[48:49], off offset:96
	v_or_b32_e32 v26, 64, v18
	v_ashrrev_i32_e32 v27, 31, v26
	v_lshlrev_b64 v[26:27], 12, v[26:27]
	v_lshl_add_u64 v[26:27], s[76:77], 0, v[26:27]
	v_lshl_add_u64 v[26:27], v[26:27], 0, v[22:23]
	global_store_dwordx2 v[26:27], v[44:45], off
	global_store_dwordx2 v[26:27], v[40:41], off offset:32
	global_store_dwordx2 v[26:27], v[36:37], off offset:64
	global_store_dwordx2 v[26:27], v[32:33], off offset:96
	v_or_b32_e32 v26, 0x50, v18
	v_ashrrev_i32_e32 v27, 31, v26
	v_lshlrev_b64 v[26:27], 12, v[26:27]
	v_lshl_add_u64 v[26:27], s[76:77], 0, v[26:27]
	v_lshl_add_u64 v[26:27], v[26:27], 0, v[22:23]
	global_store_dwordx2 v[26:27], v[28:29], off
	global_store_dwordx2 v[26:27], v[24:25], off offset:32
	global_store_dwordx2 v[26:27], v[20:21], off offset:64
	global_store_dwordx2 v[26:27], v[16:17], off offset:96
	v_or_b32_e32 v26, 0x60, v18
	v_ashrrev_i32_e32 v27, 31, v26
	v_lshlrev_b64 v[26:27], 12, v[26:27]
	v_lshl_add_u64 v[26:27], s[76:77], 0, v[26:27]
	v_or_b32_e32 v18, 0x70, v18
	v_lshl_add_u64 v[26:27], v[26:27], 0, v[22:23]
	v_ashrrev_i32_e32 v19, 31, v18
	global_store_dwordx2 v[26:27], v[12:13], off
	global_store_dwordx2 v[26:27], v[14:15], off offset:32
	global_store_dwordx2 v[26:27], v[8:9], off offset:64
	global_store_dwordx2 v[26:27], v[10:11], off offset:96
	v_lshlrev_b64 v[18:19], 12, v[18:19]
	v_lshl_add_u64 v[18:19], s[76:77], 0, v[18:19]
	s_load_dwordx16 s[64:79], s[0:1], 0x100
	v_lshl_add_u64 v[18:19], v[18:19], 0, v[22:23]
	s_mov_b64 s[42:43], 0
	global_store_dwordx2 v[18:19], v[2:3], off
	global_store_dwordx2 v[18:19], v[6:7], off offset:32
	global_store_dwordx2 v[18:19], v[0:1], off offset:64
	global_store_dwordx2 v[18:19], v[4:5], off offset:96

.LBB1_1179:
	v_mov_b32_e32 v138, v162
	s_lshl_b32 s6, s5, 8
	v_readfirstlane_b32 s7, v138
	v_lshrrev_b32_e32 v0, 3, v138
	v_and_b32_e32 v0, 6, v0
	s_movk_i32 s11, 0x78
	s_and_b32 s9, s7, 0xffffffc0
	s_waitcnt lgkmcnt(0)
	v_bfe_u32 v2, v138, 2, 4
	v_lshrrev_b32_e64 v0, v0, s11
	s_add_i32 s9, s9, s6
	v_xor_b32_e32 v3, v0, v138
	v_or_b32_e32 v0, s9, v2
	v_ashrrev_i32_e32 v1, 31, v0
	v_lshlrev_b64 v[0:1], 11, v[0:1]
	v_lshlrev_b32_e32 v3, 4, v3
	s_lshl_b32 s30, s4, 7
	v_lshl_add_u64 v[0:1], s[74:75], 0, v[0:1]
	v_and_b32_e32 v128, 48, v3
	s_load_dwordx16 s[80:95], s[0:1], 0xc0
	s_ashr_i32 s8, s7, 6
	v_lshl_add_u64 v[130:131], v[0:1], 0, v[128:129]
	v_or_b32_e32 v0, s30, v2
	v_lshl_add_u32 v0, s8, 5, v0
	v_ashrrev_i32_e32 v1, 31, v0
	v_lshlrev_b64 v[0:1], 11, v[0:1]
	s_waitcnt lgkmcnt(0)
	v_lshl_add_u64 v[0:1], s[84:85], 0, v[0:1]
	v_lshl_add_u64 v[132:133], v[0:1], 0, v[128:129]
	v_lshrrev_b32_e32 v0, 1, v138
	v_and_b32_e32 v0, 6, v0
	v_bfe_u32 v140, v138, 4, 2
	s_lshl_b32 s9, s8, 12
	v_lshrrev_b32_e64 v0, v0, s11
	v_and_b32_e32 v139, 15, v138
	s_lshl_b32 s10, s8, 11
	s_and_b32 s8, s7, 0xffffff80
	v_bitop3_b32 v0, v0, v140, 3 bitop3:0x6c
	s_and_b32 s7, s7, 64
	s_add_i32 s11, s9, 16
	v_lshlrev_b32_e32 v134, 4, v0
	v_or_b32_e32 v0, s7, v139
	s_mov_b32 m0, s11
	v_lshlrev_b32_e32 v135, 6, v0
	s_barrier
	v_lshl_add_u64 v[0:1], v[130:131], 0, s[34:35]
	s_add_i32 m0, s11, 0x400
	s_mov_b64 s[12:13], 0x10000
	v_lshl_add_u64 v[0:1], v[130:131], 0, s[12:13]
	s_add_i32 m0, s11, 0x800
	s_mov_b64 s[12:13], 0x18000
	v_lshl_add_u64 v[0:1], v[130:131], 0, s[12:13]
	s_add_i32 m0, s11, 0xc00
	s_sub_i32 s12, s11, s10
	s_add_i32 m0, s12, 0x4000
	v_lshl_add_u64 v[0:1], v[132:133], 0, s[34:35]
	s_add_i32 m0, s12, 0x4400
	s_mov_b64 s[14:15], 0x8040
	v_lshl_add_u64 v[0:1], v[130:131], 0, 64
	s_add_i32 m0, s11, 0x6000
	s_mov_b64 s[16:17], 0x10040
	v_lshl_add_u64 v[0:1], v[130:131], 0, s[14:15]
	s_add_i32 m0, s11, 0x6400
	v_or_b32_e32 v141, s8, v139
	v_lshl_add_u64 v[0:1], v[130:131], 0, s[16:17]
	s_add_i32 m0, s11, 0x6800
	s_mov_b64 s[16:17], 0x18040
	v_lshl_add_u64 v[0:1], v[130:131], 0, s[16:17]
	s_add_i32 m0, s11, 0x6c00
	v_lshlrev_b32_e32 v128, 6, v141
	v_lshl_add_u64 v[0:1], v[132:133], 0, 64
	s_add_i32 m0, s12, 0xa000
	s_mov_b32 s11, 0
	v_lshl_add_u64 v[0:1], v[132:133], 0, s[14:15]
	s_add_i32 m0, s12, 0xa400
	s_mov_b32 s12, 0
	v_mov_b32_e32 v0, 0
	v_mov_b32_e32 v1, v0
	v_mov_b32_e32 v2, v0
	v_mov_b32_e32 v3, v0
	v_mov_b32_e32 v4, v0
	v_mov_b32_e32 v5, v0
	v_mov_b32_e32 v6, v0
	v_mov_b32_e32 v7, v0
	v_mov_b32_e32 v8, v0
	v_mov_b32_e32 v9, v0
	v_mov_b32_e32 v10, v0
	v_mov_b32_e32 v11, v0
	v_mov_b32_e32 v12, v0
	v_mov_b32_e32 v13, v0
	v_mov_b32_e32 v14, v0
	v_mov_b32_e32 v15, v0
	v_mov_b32_e32 v16, v0
	v_mov_b32_e32 v17, v0
	v_mov_b32_e32 v18, v0
	v_mov_b32_e32 v19, v0
	v_mov_b32_e32 v20, v0
	v_mov_b32_e32 v21, v0
	v_mov_b32_e32 v22, v0
	v_mov_b32_e32 v23, v0
	v_mov_b32_e32 v24, v0
	v_mov_b32_e32 v25, v0
	v_mov_b32_e32 v26, v0
	v_mov_b32_e32 v27, v0
	v_mov_b32_e32 v28, v0
	v_mov_b32_e32 v29, v0
	v_mov_b32_e32 v30, v0
	v_mov_b32_e32 v31, v0
	v_mov_b32_e32 v32, v0
	v_mov_b32_e32 v33, v0
	v_mov_b32_e32 v34, v0
	v_mov_b32_e32 v35, v0
	v_mov_b32_e32 v36, v0
	v_mov_b32_e32 v37, v0
	v_mov_b32_e32 v38, v0
	v_mov_b32_e32 v39, v0
	v_mov_b32_e32 v40, v0
	v_mov_b32_e32 v41, v0
	v_mov_b32_e32 v42, v0
	v_mov_b32_e32 v43, v0
	v_mov_b32_e32 v44, v0
	v_mov_b32_e32 v45, v0
	v_mov_b32_e32 v46, v0
	v_mov_b32_e32 v47, v0
	v_mov_b32_e32 v48, v0
	v_mov_b32_e32 v49, v0
	v_mov_b32_e32 v50, v0
	v_mov_b32_e32 v51, v0
	v_mov_b32_e32 v68, v0
	v_mov_b32_e32 v69, v0
	v_mov_b32_e32 v70, v0
	v_mov_b32_e32 v71, v0
	v_mov_b32_e32 v72, v0
	v_mov_b32_e32 v73, v0
	v_mov_b32_e32 v74, v0
	v_mov_b32_e32 v75, v0
	v_mov_b32_e32 v76, v0
	v_mov_b32_e32 v77, v0
	v_mov_b32_e32 v78, v0
	v_mov_b32_e32 v79, v0
	v_mov_b32_e32 v80, v0
	v_mov_b32_e32 v81, v0
	v_mov_b32_e32 v82, v0
	v_mov_b32_e32 v83, v0
	v_mov_b32_e32 v84, v0
	v_mov_b32_e32 v85, v0
	v_mov_b32_e32 v86, v0
	v_mov_b32_e32 v87, v0
	v_mov_b32_e32 v88, v0
	v_mov_b32_e32 v89, v0
	v_mov_b32_e32 v90, v0
	v_mov_b32_e32 v91, v0
	v_mov_b32_e32 v92, v0
	v_mov_b32_e32 v93, v0
	v_mov_b32_e32 v94, v0
	v_mov_b32_e32 v95, v0
	v_mov_b32_e32 v96, v0
	v_mov_b32_e32 v97, v0
	v_mov_b32_e32 v98, v0
	v_mov_b32_e32 v99, v0
	v_mov_b32_e32 v100, v0
	v_mov_b32_e32 v101, v0
	v_mov_b32_e32 v102, v0
	v_mov_b32_e32 v103, v0
	v_mov_b32_e32 v104, v0
	v_mov_b32_e32 v105, v0
	v_mov_b32_e32 v106, v0
	v_mov_b32_e32 v107, v0
	v_mov_b32_e32 v108, v0
	v_mov_b32_e32 v109, v0
	v_mov_b32_e32 v110, v0
	v_mov_b32_e32 v111, v0
	v_mov_b32_e32 v112, v0
	v_mov_b32_e32 v113, v0
	v_mov_b32_e32 v114, v0
	v_mov_b32_e32 v115, v0
	v_mov_b32_e32 v116, v0
	v_mov_b32_e32 v117, v0
	v_mov_b32_e32 v118, v0
	v_mov_b32_e32 v119, v0
	v_mov_b32_e32 v120, v0
	v_mov_b32_e32 v121, v0
	v_mov_b32_e32 v122, v0
	v_mov_b32_e32 v123, v0
	v_mov_b32_e32 v124, v0
	v_mov_b32_e32 v125, v0
	v_mov_b32_e32 v126, v0
	v_mov_b32_e32 v127, v0
	v_mov_b32_e32 v60, v0
	v_mov_b32_e32 v61, v0
	v_mov_b32_e32 v62, v0
	v_mov_b32_e32 v63, v0
	v_mov_b32_e32 v64, v0
	v_mov_b32_e32 v65, v0
	v_mov_b32_e32 v66, v0
	v_mov_b32_e32 v67, v0
	v_mov_b32_e32 v52, v0
	v_mov_b32_e32 v53, v0
	v_mov_b32_e32 v54, v0
	v_mov_b32_e32 v55, v0
	v_mov_b32_e32 v56, v0
	v_mov_b32_e32 v57, v0
	v_mov_b32_e32 v58, v0
	v_mov_b32_e32 v59, v0
	s_mov_b64 s[16:17], 0x10080
	v_and_b32_e32 v204, 15, v168
	v_lshrrev_b32_e32 v205, 4, v168
	v_bfe_u32 v206, v168, 1, 3
	v_xor_b32_e32 v205, v205, v206
	v_lshlrev_b32_e32 v205, 4, v205
	v_readfirstlane_b32 s15, v162
	v_readfirstlane_b32 s18, v130
	v_readfirstlane_b32 s19, v131
	v_readfirstlane_b32 s28, v132
	v_readfirstlane_b32 s29, v133
	s_lshr_b32 s15, s15, 6
	s_lshl_b32 s54, s15, 12
	s_lshr_b32 s41, s15, 1
	s_and_b32 s42, s15, 1
	v_lshl_add_u32 v206, s41, 6, v204
	v_lshl_add_u32 v196, v206, 7, v205
	v_xor_b32_e32 v197, 64, v196
	v_lshl_add_u32 v206, s42, 6, v204
	v_lshl_add_u32 v198, v206, 7, v205
	v_xor_b32_e32 v199, 64, v198
	v_add_u32_e32 v198, 0xc010, v198
	v_add_u32_e32 v199, 0xc010, v199
	v_lshrrev_b32_e32 v206, 3, v168
	v_and_b32_e32 v207, 7, v168
	v_lshrrev_b32_e32 v204, 1, v206
	v_xor_b32_e32 v207, v207, v204
	v_lshlrev_b32_e32 v207, 4, v207
	v_lshl_add_u32 v200, v206, 11, v207
	v_xor_b32_e32 v201, 64, v200
	s_lshl_b32 s42, s42, 16
	s_sub_u32 s18, s18, s42
	s_subb_u32 s19, s19, 0
	s_add_i32 s41, s54, 16
	s_add_i32 m0, s41, 0x0
	s_nop 0
	global_load_lds_dwordx4 v200, s[18:19]
	s_add_i32 m0, s41, 0x400
	s_add_u32 s52, s18, 0x4000
	s_addc_u32 s53, s19, 0
	global_load_lds_dwordx4 v201, s[52:53]
	s_add_i32 m0, s41, 0x800
	s_add_u32 s52, s18, 0x8000
	s_addc_u32 s53, s19, 0
	global_load_lds_dwordx4 v200, s[52:53]
	s_add_i32 m0, s41, 0xc00
	s_add_u32 s52, s18, 0xc000
	s_addc_u32 s53, s19, 0
	global_load_lds_dwordx4 v201, s[52:53]
	s_add_i32 m0, s54, 0xc010
	s_nop 0
	global_load_lds_dwordx4 v200, s[28:29]
	s_add_i32 m0, s54, 0xc410
	s_add_u32 s52, s28, 0x4000
	s_addc_u32 s53, s29, 0
	global_load_lds_dwordx4 v201, s[52:53]
	s_add_i32 m0, s54, 0xc810
	s_add_u32 s52, s28, 0x8000
	s_addc_u32 s53, s29, 0
	global_load_lds_dwordx4 v200, s[52:53]
	s_add_i32 m0, s54, 0xcc10
	s_add_u32 s52, s28, 0xc000
	s_addc_u32 s53, s29, 0
	global_load_lds_dwordx4 v201, s[52:53]
	s_add_u32 s50, s18, 0x20000
	s_addc_u32 s51, s19, 0
	s_add_i32 m0, s41, 0x4000
	s_nop 0
	global_load_lds_dwordx4 v200, s[50:51]
	s_add_i32 m0, s41, 0x4400
	s_add_u32 s52, s50, 0x4000
	s_addc_u32 s53, s51, 0
	global_load_lds_dwordx4 v201, s[52:53]
	s_add_i32 m0, s41, 0x4800
	s_add_u32 s52, s50, 0x8000
	s_addc_u32 s53, s51, 0
	global_load_lds_dwordx4 v200, s[52:53]
	s_add_i32 m0, s41, 0x4c00
	s_add_u32 s52, s50, 0xc000
	s_addc_u32 s53, s51, 0
	global_load_lds_dwordx4 v201, s[52:53]
	s_mov_b32 s13, 0
	s_mov_b32 s14, 0
	s_setprio 1
.LBB1_1180:
	s_mul_i32 s15, s13, 0x4000
	s_add_i32 s15, s15, 16
	s_add_i32 s41, s13, 2
	s_cmp_ge_u32 s41, 3
	s_cselect_b32 s42, 3, 0
	s_sub_i32 s41, s41, s42
	s_mul_i32 s41, s41, 0x4000
	s_add_i32 s41, s41, 16
	s_add_i32 s41, s41, s54
	s_add_i32 s32, s14, 1
	s_min_u32 s32, s32, 15
	s_lshl_b32 s32, s32, 7
	s_add_u32 s50, s18, s32
	s_addc_u32 s51, s19, 0
	s_waitcnt vmcnt(4)
	s_barrier
	v_add_u32_e32 v202, s15, v196
	v_add_u32_e32 v203, s15, v197
	ds_read_b128 v[142:145], v198 offset:0
	ds_read_b128 v[146:149], v198 offset:2048
	ds_read_b128 v[150:153], v198 offset:4096
	ds_read_b128 v[154:157], v198 offset:6144
	ds_read_b128 v[158:161], v202
	ds_read_b128 v[216:219], v199 offset:0
	ds_read_b128 v[220:223], v199 offset:2048
	ds_read_b128 v[224:227], v199 offset:4096
	ds_read_b128 v[228:231], v199 offset:6144
	ds_read_b128 v[188:191], v203
	ds_read_b128 v[192:195], v202 offset:2048
	ds_read_b128 v[208:211], v203 offset:2048
	s_waitcnt lgkmcnt(7)
	s_add_i32 m0, s41, 0x0
	v_mfma_f32_16x16x32_bf16 v[124:127], v[142:145], v[158:161], v[124:127]
	v_mfma_f32_16x16x32_bf16 v[120:123], v[146:149], v[158:161], v[120:123]
	v_mfma_f32_16x16x32_bf16 v[116:119], v[150:153], v[158:161], v[116:119]
	v_mfma_f32_16x16x32_bf16 v[112:115], v[154:157], v[158:161], v[112:115]
	ds_read_b128 v[158:161], v202 offset:4096
	global_load_lds_dwordx4 v200, s[50:51]
	s_waitcnt lgkmcnt(3)
	s_add_i32 m0, s41, 0x400
	s_add_u32 s52, s50, 0x4000
	s_addc_u32 s53, s51, 0
	v_mfma_f32_16x16x32_bf16 v[124:127], v[216:219], v[188:191], v[124:127]
	v_mfma_f32_16x16x32_bf16 v[120:123], v[220:223], v[188:191], v[120:123]
	v_mfma_f32_16x16x32_bf16 v[116:119], v[224:227], v[188:191], v[116:119]
	v_mfma_f32_16x16x32_bf16 v[112:115], v[228:231], v[188:191], v[112:115]
	ds_read_b128 v[188:191], v203 offset:4096
	global_load_lds_dwordx4 v201, s[52:53]
	s_waitcnt lgkmcnt(3)
	s_add_i32 m0, s41, 0x800
	s_add_u32 s52, s50, 0x8000
	s_addc_u32 s53, s51, 0
	v_mfma_f32_16x16x32_bf16 v[108:111], v[142:145], v[192:195], v[108:111]
	v_mfma_f32_16x16x32_bf16 v[104:107], v[146:149], v[192:195], v[104:107]
	v_mfma_f32_16x16x32_bf16 v[100:103], v[150:153], v[192:195], v[100:103]
	v_mfma_f32_16x16x32_bf16 v[96:99], v[154:157], v[192:195], v[96:99]
	ds_read_b128 v[192:195], v202 offset:6144
	global_load_lds_dwordx4 v200, s[52:53]
	s_waitcnt lgkmcnt(3)
	s_add_i32 m0, s41, 0xc00
	s_add_u32 s52, s50, 0xc000
	s_addc_u32 s53, s51, 0
	v_mfma_f32_16x16x32_bf16 v[108:111], v[216:219], v[208:211], v[108:111]
	v_mfma_f32_16x16x32_bf16 v[104:107], v[220:223], v[208:211], v[104:107]
	v_mfma_f32_16x16x32_bf16 v[100:103], v[224:227], v[208:211], v[100:103]
	v_mfma_f32_16x16x32_bf16 v[96:99], v[228:231], v[208:211], v[96:99]
	ds_read_b128 v[208:211], v203 offset:6144
	global_load_lds_dwordx4 v201, s[52:53]
	s_waitcnt lgkmcnt(3)
	v_mfma_f32_16x16x32_bf16 v[92:95], v[142:145], v[158:161], v[92:95]
	v_mfma_f32_16x16x32_bf16 v[88:91], v[146:149], v[158:161], v[88:91]
	v_mfma_f32_16x16x32_bf16 v[84:87], v[150:153], v[158:161], v[84:87]
	v_mfma_f32_16x16x32_bf16 v[80:83], v[154:157], v[158:161], v[80:83]
	s_waitcnt lgkmcnt(2)
	v_mfma_f32_16x16x32_bf16 v[92:95], v[216:219], v[188:191], v[92:95]
	v_mfma_f32_16x16x32_bf16 v[88:91], v[220:223], v[188:191], v[88:91]
	v_mfma_f32_16x16x32_bf16 v[84:87], v[224:227], v[188:191], v[84:87]
	v_mfma_f32_16x16x32_bf16 v[80:83], v[228:231], v[188:191], v[80:83]
	s_waitcnt lgkmcnt(1)
	v_mfma_f32_16x16x32_bf16 v[76:79], v[142:145], v[192:195], v[76:79]
	v_mfma_f32_16x16x32_bf16 v[72:75], v[146:149], v[192:195], v[72:75]
	v_mfma_f32_16x16x32_bf16 v[68:71], v[150:153], v[192:195], v[68:71]
	v_mfma_f32_16x16x32_bf16 v[48:51], v[154:157], v[192:195], v[48:51]
	s_waitcnt lgkmcnt(0)
	v_mfma_f32_16x16x32_bf16 v[76:79], v[216:219], v[208:211], v[76:79]
	v_mfma_f32_16x16x32_bf16 v[72:75], v[220:223], v[208:211], v[72:75]
	v_mfma_f32_16x16x32_bf16 v[68:71], v[224:227], v[208:211], v[68:71]
	v_mfma_f32_16x16x32_bf16 v[48:51], v[228:231], v[208:211], v[48:51]
	s_add_i32 s42, s13, 1
	s_cmp_lg_u32 s13, 2
	s_cselect_b32 s13, s42, 0
	s_mul_i32 s15, s13, 0x4000
	s_add_i32 s15, s15, 16
	s_add_i32 s41, s13, 2
	s_cmp_ge_u32 s41, 3
	s_cselect_b32 s42, 3, 0
	s_sub_i32 s41, s41, s42
	s_mul_i32 s41, s41, 0x4000
	s_add_i32 s41, s41, 16
	s_add_i32 s41, s41, s54
	s_add_u32 s50, s18, s32
	s_addc_u32 s51, s19, 0
	s_add_u32 s50, s50, 0x20000
	s_addc_u32 s51, s51, 0
	s_add_u32 s46, s28, s32
	s_addc_u32 s47, s29, 0
	s_waitcnt vmcnt(4)
	s_barrier
	v_add_u32_e32 v202, s15, v196
	v_add_u32_e32 v203, s15, v197
	ds_read_b128 v[158:161], v202
	ds_read_b128 v[188:191], v203
	ds_read_b128 v[192:195], v202 offset:2048
	ds_read_b128 v[208:211], v203 offset:2048
	s_waitcnt lgkmcnt(3)
	s_add_i32 m0, s54, 0xc010
	v_mfma_f32_16x16x32_bf16 v[44:47], v[142:145], v[158:161], v[44:47]
	v_mfma_f32_16x16x32_bf16 v[40:43], v[146:149], v[158:161], v[40:43]
	v_mfma_f32_16x16x32_bf16 v[36:39], v[150:153], v[158:161], v[36:39]
	v_mfma_f32_16x16x32_bf16 v[32:35], v[154:157], v[158:161], v[32:35]
	ds_read_b128 v[158:161], v202 offset:4096
	global_load_lds_dwordx4 v200, s[46:47]
	s_waitcnt lgkmcnt(3)
	s_add_i32 m0, s54, 0xc410
	s_add_u32 s52, s46, 0x4000
	s_addc_u32 s53, s47, 0
	v_mfma_f32_16x16x32_bf16 v[44:47], v[216:219], v[188:191], v[44:47]
	v_mfma_f32_16x16x32_bf16 v[40:43], v[220:223], v[188:191], v[40:43]
	v_mfma_f32_16x16x32_bf16 v[36:39], v[224:227], v[188:191], v[36:39]
	v_mfma_f32_16x16x32_bf16 v[32:35], v[228:231], v[188:191], v[32:35]
	ds_read_b128 v[188:191], v203 offset:4096
	global_load_lds_dwordx4 v201, s[52:53]
	s_waitcnt lgkmcnt(3)
	s_add_i32 m0, s54, 0xc810
	s_add_u32 s52, s46, 0x8000
	s_addc_u32 s53, s47, 0
	v_mfma_f32_16x16x32_bf16 v[28:31], v[142:145], v[192:195], v[28:31]
	v_mfma_f32_16x16x32_bf16 v[24:27], v[146:149], v[192:195], v[24:27]
	v_mfma_f32_16x16x32_bf16 v[20:23], v[150:153], v[192:195], v[20:23]
	v_mfma_f32_16x16x32_bf16 v[16:19], v[154:157], v[192:195], v[16:19]
	ds_read_b128 v[192:195], v202 offset:6144
	global_load_lds_dwordx4 v200, s[52:53]
	s_waitcnt lgkmcnt(3)
	s_add_i32 m0, s54, 0xcc10
	s_add_u32 s52, s46, 0xc000
	s_addc_u32 s53, s47, 0
	v_mfma_f32_16x16x32_bf16 v[28:31], v[216:219], v[208:211], v[28:31]
	v_mfma_f32_16x16x32_bf16 v[24:27], v[220:223], v[208:211], v[24:27]
	v_mfma_f32_16x16x32_bf16 v[20:23], v[224:227], v[208:211], v[20:23]
	v_mfma_f32_16x16x32_bf16 v[16:19], v[228:231], v[208:211], v[16:19]
	ds_read_b128 v[208:211], v203 offset:6144
	global_load_lds_dwordx4 v201, s[52:53]
	s_waitcnt lgkmcnt(3)
	s_add_i32 m0, s41, 0x0
	v_mfma_f32_16x16x32_bf16 v[12:15], v[142:145], v[158:161], v[12:15]
	v_mfma_f32_16x16x32_bf16 v[8:11], v[146:149], v[158:161], v[8:11]
	v_mfma_f32_16x16x32_bf16 v[4:7], v[150:153], v[158:161], v[4:7]
	v_mfma_f32_16x16x32_bf16 v[0:3], v[154:157], v[158:161], v[0:3]
	global_load_lds_dwordx4 v200, s[50:51]
	s_waitcnt lgkmcnt(2)
	s_add_i32 m0, s41, 0x400
	s_add_u32 s52, s50, 0x4000
	s_addc_u32 s53, s51, 0
	v_mfma_f32_16x16x32_bf16 v[12:15], v[216:219], v[188:191], v[12:15]
	v_mfma_f32_16x16x32_bf16 v[8:11], v[220:223], v[188:191], v[8:11]
	v_mfma_f32_16x16x32_bf16 v[4:7], v[224:227], v[188:191], v[4:7]
	v_mfma_f32_16x16x32_bf16 v[0:3], v[228:231], v[188:191], v[0:3]
	global_load_lds_dwordx4 v201, s[52:53]
	s_waitcnt lgkmcnt(1)
	s_add_i32 m0, s41, 0x800
	s_add_u32 s52, s50, 0x8000
	s_addc_u32 s53, s51, 0
	v_mfma_f32_16x16x32_bf16 v[60:63], v[142:145], v[192:195], v[60:63]
	v_mfma_f32_16x16x32_bf16 v[64:67], v[146:149], v[192:195], v[64:67]
	v_mfma_f32_16x16x32_bf16 v[52:55], v[150:153], v[192:195], v[52:55]
	v_mfma_f32_16x16x32_bf16 v[56:59], v[154:157], v[192:195], v[56:59]
	global_load_lds_dwordx4 v200, s[52:53]
	s_waitcnt lgkmcnt(0)
	s_add_i32 m0, s41, 0xc00
	s_add_u32 s52, s50, 0xc000
	s_addc_u32 s53, s51, 0
	v_mfma_f32_16x16x32_bf16 v[60:63], v[216:219], v[208:211], v[60:63]
	v_mfma_f32_16x16x32_bf16 v[64:67], v[220:223], v[208:211], v[64:67]
	v_mfma_f32_16x16x32_bf16 v[52:55], v[224:227], v[208:211], v[52:55]
	v_mfma_f32_16x16x32_bf16 v[56:59], v[228:231], v[208:211], v[56:59]
	global_load_lds_dwordx4 v201, s[52:53]
	s_add_i32 s42, s13, 1
	s_cmp_lg_u32 s13, 2
	s_cselect_b32 s13, s42, 0
	s_add_i32 s14, s14, 1
	s_cmp_eq_u32 s14, 16
	s_cbranch_scc0 .LBB1_1180
	s_setprio 0
	s_waitcnt vmcnt(0)
	s_waitcnt vmcnt(0)
	s_barrier
	s_load_dwordx8 s[80:87], s[0:1], 0x180
	s_cmp_lt_i32 s4, 64
	v_readlane_b32 s12, v242, 9
	s_cselect_b64 s[10:11], -1, 0
	v_readlane_b32 s13, v242, 10
	s_and_b64 s[10:11], s[12:13], s[10:11]
	s_mov_b64 s[38:39], -1
	s_and_b64 vcc, exec, s[10:11]
	s_movk_i32 s12, 0x2020
	s_cbranch_vccnz .LBB1_1291
	v_or_b32_e32 v128, s6, v139
	v_add_u32_e32 v132, s8, v128
	v_lshl_or_b32 v128, v140, 2, s30
	v_or_b32_e32 v130, s7, v128
	v_lshlrev_b32_e32 v134, 5, v132
	s_movk_i32 s8, 0x1fff
	v_ashrrev_i32_e32 v135, 31, v134
	v_cmp_lt_i32_e32 vcc, s8, v130
	s_and_saveexec_b64 s[8:9], vcc
	s_xor_b64 s[40:41], exec, s[8:9]
	s_cbranch_execz .LBB1_1186
	v_cmp_gt_u32_e64 s[38:39], s12, v130
	s_and_saveexec_b64 s[42:43], s[38:39]
	s_cbranch_execz .LBB1_1185
	v_add_u32_e32 v128, 0xffffe000, v130
	v_lshl_add_u64 v[136:137], v[134:135], 2, s[78:79]
	v_lshlrev_b64 v[142:143], 2, v[128:129]
	v_lshl_add_u64 v[136:137], v[136:137], 0, v[142:143]
	v_lshl_add_u64 v[142:143], s[22:23], 0, v[142:143]
	global_load_dwordx4 v[142:145], v[142:143], off
	s_waitcnt vmcnt(0)
	v_pk_add_f32 v[144:145], v[126:127], v[144:145]
	v_pk_add_f32 v[142:143], v[124:125], v[142:143]
	global_store_dwordx4 v[136:137], v[142:145], off
